# attention: QK accumulators initialised with -running_max (persistent 16-VGPR tuple) so the common path needs no v_sub before v_exp; subs only in the rescale path (on v53)
# speedup vs baseline: 1.0005x; 1.0005x over previous
; #define ATT_ISSUE(tilebase, bufbase) do { const unsigned char* _tb = (tilebase); asm volatile("" : "+s"(_tb)); _Pragma("unroll") for (int _i = 0; _i < 6; ++_i) { int _q = wave + 8 * _i; _q = _q > 44 ? 44 : _q; \
;         __builtin_amdgcn_global_load_lds((const unsigned*)(_tb + goff[_i]), (LAS unsigned*)((bufbase) + _q * 1024), 16, 0, 0); } } while (0)
; #define ATT_BAR() do { asm volatile("s_waitcnt vmcnt(0) lgkmcnt(0)" ::: "memory"); __builtin_amdgcn_s_barrier(); asm volatile("" ::: "memory"); } while (0)
; __device__ __forceinline__ void att_mfma(const Params& P, LAS unsigned char* lds, int wave) {
;     ...
;     for (int u = blockIdx.x; u < 1024; u += gridDim.x) {
;         const int bh = u & 63, r = u >> 6, kk = r >> 2, j4 = r & 3;
;         const int qb = kk == 0 ? j4 : (kk == 1 ? 15 - j4 : (kk == 2 ? 4 + j4 : 11 - j4));
;         const int b = bh >> 3, hh = bh & 7;
;         const int ntile = 4 * qb + 4, my_last = 4 * qb + w4;
;         const size_t qrow_g = (size_t)b * SEQ + qb * 256 + w4 * 64 + (wave >> 2) * 32 + q32;
;         const unsigned char* kvb = (const unsigned char*)(KV + (size_t)b * SEQ * 2560 + hh * 320);
;         ATT_ISSUE(kvb, lds);
;         bf16x8 qf[12];
;         { const bf16_t* qp = Q + qrow_g * 1536 + hh * 192 + hf * 8;
; #pragma unroll
;           for (int ks = 0; ks < 12; ++ks) qf[ks] = *(const bf16x8*)(qp + ks * 16); }
;         f32x16 o[4];
; #pragma unroll
;         for (int d = 0; d < 4; ++d)
; #pragma unroll
;             for (int i = 0; i < 16; ++i) o[d][i] = 0.f;
;         float mrun = -1e30f, lrun = 0.f;
;         bf16x8 pb[4];
; #pragma unroll
;         for (int i = 0; i < 4; ++i) pb[i] = (bf16x8){0, 0, 0, 0, 0, 0, 0, 0};
;         ATT_BAR();
; #pragma unroll
;         for (int ks = 0; ks < 12; ++ks) asm volatile("" : "+v"(qf[ks]));
;         {
;             float qv[12][8]; float sq = 0.f;
; #pragma unroll
;             for (int ks = 0; ks < 12; ++ks)
; #pragma unroll
;                 for (int e = 0; e < 8; ++e) { qv[ks][e] = bf2f((unsigned short)qf[ks][e]); sq += qv[ks][e] * qv[ks][e]; }
.LBB0_1014:
	s_bfe_u32 s5, s73, 0x3000c
	s_and_b32 s6, s38, 7
	s_mul_i32 s5, s5, 0x1400000
	s_mulk_i32 s6, 0x280
	s_or_b32 s5, s5, s6
	s_add_u32 s10, s25, s5
	s_addc_u32 s11, s26, 0
	s_lshl_b32 s5, s39, 9
	s_lshl_b32 s51, s4, 2
	s_and_b32 s6, s5, 0x7000
	s_and_b32 s47, s39, 7
	s_add_i32 s50, s51, 4
	s_lshl_b32 s16, s4, 8
	s_mul_i32 s4, s6, 0x1400
	s_add_u32 s4, s48, s4
	s_addc_u32 s5, s49, 0
	s_mul_i32 s17, s47, 0x280
	s_add_u32 s4, s4, s17
	s_addc_u32 s5, s5, 0
	s_add_i32 s16, s16, s6
	v_add_u32_e32 v164, s16, v224
	s_mul_i32 s6, s47, 0x180
	s_mov_b32 s17, 2
	s_mov_b32 s61, 1
	s_mov_b32 s16, 0
	s_mov_b32 s74, 0
	s_movk_i32 s75, 0x6400
	s_mov_b32 s76, 0xc800
	s_mov_b32 s78, 0xc800
	s_mov_b32 s79, 0x11800
	s_mov_b32 s80, 0x16800
	s_mov_b32 s77, 0x1b800
	s_add_u32 s10, s10, 0x50000
	s_addc_u32 s11, s11, 0
	s_cmp_eq_u32 s33, 0
	s_cselect_b32 s82, s74, s78
	s_add_i32 m0, s74, s19
	v_lshl_add_u64 v[0:1], s[4:5], 0, v[144:145]
	global_load_lds_dwordx4 v[0:1], off
	s_add_i32 m0, s74, s20
	v_lshl_add_u64 v[0:1], s[4:5], 0, v[146:147]
	global_load_lds_dwordx4 v[0:1], off
	s_add_i32 m0, s74, s21
	v_lshl_add_u64 v[0:1], s[4:5], 0, v[148:149]
	global_load_lds_dwordx4 v[0:1], off
	s_add_i32 m0, s82, s22
	v_lshl_add_u64 v[0:1], s[4:5], 0, v[150:151]
	global_load_lds_dwordx4 v[0:1], off
	s_add_i32 m0, s78, s23
	v_lshl_add_u64 v[0:1], s[4:5], 0, v[156:157]
	global_load_lds_dwordx4 v[0:1], off
	s_add_i32 m0, s78, s24
	v_lshl_add_u64 v[0:1], s[4:5], 0, v[154:155]
	global_load_lds_dwordx4 v[0:1], off
	s_add_u32 s4, s4, 0x50000
	s_addc_u32 s5, s5, 0
	s_cmp_eq_u32 s33, 0
	s_cselect_b32 s82, s75, s79
	s_add_i32 m0, s75, s19
	v_lshl_add_u64 v[0:1], s[4:5], 0, v[144:145]
	global_load_lds_dwordx4 v[0:1], off
	s_add_i32 m0, s75, s20
	v_lshl_add_u64 v[0:1], s[4:5], 0, v[146:147]
	global_load_lds_dwordx4 v[0:1], off
	s_add_i32 m0, s75, s21
	v_lshl_add_u64 v[0:1], s[4:5], 0, v[148:149]
	global_load_lds_dwordx4 v[0:1], off
	s_add_i32 m0, s82, s22
	v_lshl_add_u64 v[0:1], s[4:5], 0, v[150:151]
	global_load_lds_dwordx4 v[0:1], off
	s_add_i32 m0, s79, s23
	v_lshl_add_u64 v[0:1], s[4:5], 0, v[156:157]
	global_load_lds_dwordx4 v[0:1], off
	s_add_i32 m0, s79, s24
	v_lshl_add_u64 v[0:1], s[4:5], 0, v[154:155]
	global_load_lds_dwordx4 v[0:1], off
	v_mad_u64_u32 v[0:1], s[4:5], v164, s35, v[166:167]
	v_lshl_add_u64 v[0:1], v[0:1], 0, s[6:7]
	v_lshl_add_u64 v[0:1], v[158:159], 1, v[0:1]
	flat_load_dwordx4 v[104:107], v[0:1]
	flat_load_dwordx4 v[108:111], v[0:1] offset:32
	flat_load_dwordx4 v[112:115], v[0:1] offset:64
	flat_load_dwordx4 v[116:119], v[0:1] offset:96
	flat_load_dwordx4 v[208:211], v[0:1] offset:128
	flat_load_dwordx4 v[200:203], v[0:1] offset:160
	flat_load_dwordx4 v[192:195], v[0:1] offset:192
	flat_load_dwordx4 v[184:187], v[0:1] offset:224
	flat_load_dwordx4 v[174:177], v[0:1] offset:256
	flat_load_dwordx4 v[132:135], v[0:1] offset:288
	flat_load_dwordx4 v[178:181], v[0:1] offset:320
	flat_load_dwordx4 v[138:141], v[0:1] offset:352
	s_waitcnt vmcnt(0) lgkmcnt(0)
	s_barrier
	v_lshlrev_b32_e32 v0, 7, v164
	v_mov_b32_e32 v1, v165
	v_and_b32_e32 v0, 0x7ff80, v0
	v_lshl_add_u64 v[142:143], v[162:163], 0, v[0:1]
	v_add_co_u32_e32 v246, vcc, s36, v142
	s_or_b32 s6, s51, s18
	s_nop 0
	v_addc_co_u32_e32 v247, vcc, 0, v143, vcc
	s_add_i32 s51, s6, 1
	s_mov_b32 s58, 0
	s_waitcnt vmcnt(0) lgkmcnt(0)
	s_nop 0
	v_and_b32_e32 v235, 0xffff0000, v104
	v_lshlrev_b32_e32 v234, 16, v104
	v_mul_f32_e32 v104, v235, v235
	v_and_b32_e32 v243, 0xffff0000, v105
	v_lshlrev_b32_e32 v242, 16, v105
	v_pk_fma_f32 v[104:105], v[234:235], v[234:235], v[104:105] op_sel_hi:[1,1,0]
	v_and_b32_e32 v233, 0xffff0000, v106
	v_lshlrev_b32_e32 v232, 16, v106
	v_pk_fma_f32 v[104:105], v[242:243], v[242:243], v[104:105]
	v_mul_f32_e32 v106, v243, v243
	v_pk_add_f32 v[104:105], v[106:107], v[104:105] op_sel_hi:[0,1]
	v_pk_fma_f32 v[104:105], v[232:233], v[232:233], v[104:105]
	v_mul_f32_e32 v106, v233, v233
	v_and_b32_e32 v241, 0xffff0000, v107
	v_lshlrev_b32_e32 v240, 16, v107
	v_pk_add_f32 v[104:105], v[106:107], v[104:105] op_sel_hi:[0,1]
	v_pk_fma_f32 v[104:105], v[240:241], v[240:241], v[104:105]
	v_mul_f32_e32 v106, v241, v241
	v_and_b32_e32 v219, 0xffff0000, v111
	v_lshlrev_b32_e32 v218, 16, v111
	v_and_b32_e32 v221, 0xffff0000, v110
	v_lshlrev_b32_e32 v220, 16, v110
	v_and_b32_e32 v111, 0xffff0000, v109
	v_lshlrev_b32_e32 v110, 16, v109
	v_and_b32_e32 v109, 0xffff0000, v108
	v_lshlrev_b32_e32 v108, 16, v108
	v_pk_add_f32 v[104:105], v[106:107], v[104:105] op_sel_hi:[0,1]
	v_pk_fma_f32 v[104:105], v[108:109], v[108:109], v[104:105]
	v_mul_f32_e32 v106, v109, v109
	v_pk_add_f32 v[104:105], v[106:107], v[104:105] op_sel_hi:[0,1]
	v_pk_fma_f32 v[104:105], v[110:111], v[110:111], v[104:105]
	v_mul_f32_e32 v106, v111, v111
	v_pk_add_f32 v[104:105], v[106:107], v[104:105] op_sel_hi:[0,1]
	v_pk_fma_f32 v[104:105], v[220:221], v[220:221], v[104:105]
	v_mul_f32_e32 v106, v221, v221
	v_pk_add_f32 v[104:105], v[106:107], v[104:105] op_sel_hi:[0,1]
	v_pk_fma_f32 v[104:105], v[218:219], v[218:219], v[104:105]
	v_mul_f32_e32 v106, v219, v219
	v_and_b32_e32 v215, 0xffff0000, v115
	v_lshlrev_b32_e32 v214, 16, v115
	v_and_b32_e32 v217, 0xffff0000, v114
	v_lshlrev_b32_e32 v216, 16, v114
	v_and_b32_e32 v115, 0xffff0000, v113
	v_lshlrev_b32_e32 v114, 16, v113
	v_and_b32_e32 v113, 0xffff0000, v112
	v_lshlrev_b32_e32 v112, 16, v112
	v_pk_add_f32 v[104:105], v[106:107], v[104:105] op_sel_hi:[0,1]
	v_pk_fma_f32 v[104:105], v[112:113], v[112:113], v[104:105]
	v_mul_f32_e32 v106, v113, v113
	v_pk_add_f32 v[104:105], v[106:107], v[104:105] op_sel_hi:[0,1]
	v_pk_fma_f32 v[104:105], v[114:115], v[114:115], v[104:105]
; __device__ __forceinline__ void att_mfma(const Params& P, LAS unsigned char* lds, int wave) {
;     ...
;             float qv[12][8]; float sq = 0.f;
; #pragma unroll
;             for (int ks = 0; ks < 12; ++ks)
; #pragma unroll
;                 for (int e = 0; e < 8; ++e) { qv[ks][e] = bf2f((unsigned short)qf[ks][e]); sq += qv[ks][e] * qv[ks][e]; }
;             { const auto rr = __builtin_amdgcn_permlane32_swap(__float_as_uint(sq), __float_as_uint(sq), false, false);
;               sq = __uint_as_float(rr[0]) + __uint_as_float(rr[1]); }
;             const float rs = __builtin_amdgcn_rsqf(sq * (1.f / 192.f) + EPS) * (0.07216878364870322f * 1.4426950408889634f);
;             const float* qg = (const float*)(ws + WS_SMALL) + 2048 + 8 * hf;
;             const int spos = (int)(qrow_g & (SEQ - 1));
;             const float* cM = (const float*)(ws + WS_ROPE_M) + spos * 32 + 8 * hf; const float* sM = cM + 4096 * 32;
; #pragma unroll
;             for (int ks = 0; ks < 12; ++ks) { const f32x4 g0 = *(const f32x4*)(qg + 16 * ks), g1 = *(const f32x4*)(qg + 16 * ks + 4);
; #pragma unroll
;                 for (int e = 0; e < 4; ++e) { qv[ks][e] *= rs * g0[e]; qv[ks][4 + e] *= rs * g1[e]; } }
	v_mul_f32_e32 v106, v115, v115
	v_pk_add_f32 v[104:105], v[106:107], v[104:105] op_sel_hi:[0,1]
	v_pk_fma_f32 v[104:105], v[216:217], v[216:217], v[104:105]
	v_mul_f32_e32 v106, v217, v217
	v_pk_add_f32 v[104:105], v[106:107], v[104:105] op_sel_hi:[0,1]
	v_pk_fma_f32 v[104:105], v[214:215], v[214:215], v[104:105]
	v_mul_f32_e32 v106, v215, v215
	v_and_b32_e32 v131, 0xffff0000, v133
	v_lshlrev_b32_e32 v130, 16, v133
	v_and_b32_e32 v127, 0xffff0000, v139
	v_lshlrev_b32_e32 v126, 16, v139
	v_and_b32_e32 v137, 0xffff0000, v132
	v_lshlrev_b32_e32 v136, 16, v132
	v_and_b32_e32 v133, 0xffff0000, v138
	v_lshlrev_b32_e32 v132, 16, v138
	v_and_b32_e32 v139, 0xffff0000, v177
	v_lshlrev_b32_e32 v138, 16, v177
	v_and_b32_e32 v171, 0xffff0000, v176
	v_lshlrev_b32_e32 v170, 16, v176
	v_and_b32_e32 v173, 0xffff0000, v175
	v_lshlrev_b32_e32 v172, 16, v175
	v_and_b32_e32 v169, 0xffff0000, v179
	v_lshlrev_b32_e32 v168, 16, v179
	v_and_b32_e32 v177, 0xffff0000, v174
	v_lshlrev_b32_e32 v176, 16, v174
	v_and_b32_e32 v175, 0xffff0000, v178
	v_lshlrev_b32_e32 v174, 16, v178
	v_and_b32_e32 v179, 0xffff0000, v187
	v_lshlrev_b32_e32 v178, 16, v187
	v_and_b32_e32 v183, 0xffff0000, v186
	v_lshlrev_b32_e32 v182, 16, v186
	v_and_b32_e32 v187, 0xffff0000, v195
	v_lshlrev_b32_e32 v186, 16, v195
	v_and_b32_e32 v191, 0xffff0000, v194
	v_lshlrev_b32_e32 v190, 16, v194
	v_and_b32_e32 v195, 0xffff0000, v203
	v_lshlrev_b32_e32 v194, 16, v203
	v_and_b32_e32 v199, 0xffff0000, v202
	v_lshlrev_b32_e32 v198, 16, v202
	v_and_b32_e32 v203, 0xffff0000, v211
	v_lshlrev_b32_e32 v202, 16, v211
	v_and_b32_e32 v207, 0xffff0000, v210
	v_lshlrev_b32_e32 v206, 16, v210
	v_and_b32_e32 v211, 0xffff0000, v119
	v_lshlrev_b32_e32 v210, 16, v119
	v_and_b32_e32 v213, 0xffff0000, v118
	v_lshlrev_b32_e32 v212, 16, v118
	v_and_b32_e32 v119, 0xffff0000, v117
	v_lshlrev_b32_e32 v118, 16, v117
	v_and_b32_e32 v117, 0xffff0000, v116
	v_lshlrev_b32_e32 v116, 16, v116
	v_pk_add_f32 v[104:105], v[106:107], v[104:105] op_sel_hi:[0,1]
	v_pk_fma_f32 v[104:105], v[116:117], v[116:117], v[104:105]
	v_mul_f32_e32 v106, v117, v117
	v_pk_add_f32 v[104:105], v[106:107], v[104:105] op_sel_hi:[0,1]
	v_pk_fma_f32 v[104:105], v[118:119], v[118:119], v[104:105]
	v_mul_f32_e32 v106, v119, v119
	v_pk_add_f32 v[104:105], v[106:107], v[104:105] op_sel_hi:[0,1]
	v_pk_fma_f32 v[104:105], v[212:213], v[212:213], v[104:105]
	v_mul_f32_e32 v106, v213, v213
	v_pk_add_f32 v[104:105], v[106:107], v[104:105] op_sel_hi:[0,1]
	v_pk_fma_f32 v[104:105], v[210:211], v[210:211], v[104:105]
	v_mul_f32_e32 v106, v211, v211
	v_and_b32_e32 v205, 0xffff0000, v209
	v_lshlrev_b32_e32 v204, 16, v209
	v_and_b32_e32 v209, 0xffff0000, v208
	v_lshlrev_b32_e32 v208, 16, v208
	v_pk_add_f32 v[104:105], v[106:107], v[104:105] op_sel_hi:[0,1]
	v_pk_fma_f32 v[104:105], v[208:209], v[208:209], v[104:105]
	v_mul_f32_e32 v106, v209, v209
	v_pk_add_f32 v[104:105], v[106:107], v[104:105] op_sel_hi:[0,1]
	v_pk_fma_f32 v[104:105], v[204:205], v[204:205], v[104:105]
	v_mul_f32_e32 v106, v205, v205
	v_pk_add_f32 v[104:105], v[106:107], v[104:105] op_sel_hi:[0,1]
	v_pk_fma_f32 v[104:105], v[206:207], v[206:207], v[104:105]
	v_mul_f32_e32 v106, v207, v207
	v_pk_add_f32 v[104:105], v[106:107], v[104:105] op_sel_hi:[0,1]
	v_pk_fma_f32 v[104:105], v[202:203], v[202:203], v[104:105]
	v_mul_f32_e32 v106, v203, v203
	v_and_b32_e32 v197, 0xffff0000, v201
	v_lshlrev_b32_e32 v196, 16, v201
	v_and_b32_e32 v201, 0xffff0000, v200
	v_lshlrev_b32_e32 v200, 16, v200
	v_pk_add_f32 v[104:105], v[106:107], v[104:105] op_sel_hi:[0,1]
	v_pk_fma_f32 v[104:105], v[200:201], v[200:201], v[104:105]
	v_mul_f32_e32 v106, v201, v201
	v_pk_add_f32 v[104:105], v[106:107], v[104:105] op_sel_hi:[0,1]
	v_pk_fma_f32 v[104:105], v[196:197], v[196:197], v[104:105]
	v_mul_f32_e32 v106, v197, v197
	v_pk_add_f32 v[104:105], v[106:107], v[104:105] op_sel_hi:[0,1]
	v_pk_fma_f32 v[104:105], v[198:199], v[198:199], v[104:105]
	v_mul_f32_e32 v106, v199, v199
	v_pk_add_f32 v[104:105], v[106:107], v[104:105] op_sel_hi:[0,1]
	v_pk_fma_f32 v[104:105], v[194:195], v[194:195], v[104:105]
	v_mul_f32_e32 v106, v195, v195
	v_and_b32_e32 v189, 0xffff0000, v193
	v_lshlrev_b32_e32 v188, 16, v193
	v_and_b32_e32 v193, 0xffff0000, v192
	v_lshlrev_b32_e32 v192, 16, v192
	v_pk_add_f32 v[104:105], v[106:107], v[104:105] op_sel_hi:[0,1]
	v_pk_fma_f32 v[104:105], v[192:193], v[192:193], v[104:105]
	v_mul_f32_e32 v106, v193, v193
	flat_load_dwordx4 v[100:103], v[160:161]
	flat_load_dwordx4 v[96:99], v[160:161] offset:16
	flat_load_dwordx4 v[92:95], v[160:161] offset:64
	flat_load_dwordx4 v[88:91], v[160:161] offset:80
	flat_load_dwordx4 v[84:87], v[160:161] offset:128
	flat_load_dwordx4 v[80:83], v[160:161] offset:144
	flat_load_dwordx4 v[76:79], v[160:161] offset:192
	flat_load_dwordx4 v[72:75], v[160:161] offset:208
	flat_load_dwordx4 v[68:71], v[160:161] offset:256
	flat_load_dwordx4 v[64:67], v[160:161] offset:272
	flat_load_dwordx4 v[60:63], v[160:161] offset:320
	flat_load_dwordx4 v[56:59], v[160:161] offset:336
	flat_load_dwordx4 v[52:55], v[160:161] offset:384
	flat_load_dwordx4 v[48:51], v[160:161] offset:400
	flat_load_dwordx4 v[44:47], v[160:161] offset:448
	flat_load_dwordx4 v[40:43], v[160:161] offset:464
	flat_load_dwordx4 v[36:39], v[160:161] offset:512
	flat_load_dwordx4 v[32:35], v[160:161] offset:528
	flat_load_dwordx4 v[28:31], v[160:161] offset:576
	flat_load_dwordx4 v[24:27], v[160:161] offset:592
	flat_load_dwordx4 v[20:23], v[160:161] offset:640
	flat_load_dwordx4 v[16:19], v[160:161] offset:656
	flat_load_dwordx4 v[12:15], v[160:161] offset:704
	flat_load_dwordx4 v[8:11], v[160:161] offset:720
; __device__ __forceinline__ void att_mfma(const Params& P, LAS unsigned char* lds, int wave) {
;     ...
;                 for (int e = 0; e < 8; ++e) { qv[ks][e] = bf2f((unsigned short)qf[ks][e]); sq += qv[ks][e] * qv[ks][e]; }
;             { const auto rr = __builtin_amdgcn_permlane32_swap(__float_as_uint(sq), __float_as_uint(sq), false, false);
;               sq = __uint_as_float(rr[0]) + __uint_as_float(rr[1]); }
;             const float rs = __builtin_amdgcn_rsqf(sq * (1.f / 192.f) + EPS) * (0.07216878364870322f * 1.4426950408889634f);
;             const float* qg = (const float*)(ws + WS_SMALL) + 2048 + 8 * hf;
;             const int spos = (int)(qrow_g & (SEQ - 1));
;             const float* cM = (const float*)(ws + WS_ROPE_M) + spos * 32 + 8 * hf; const float* sM = cM + 4096 * 32;
; #pragma unroll
;             for (int ks = 0; ks < 12; ++ks) { const f32x4 g0 = *(const f32x4*)(qg + 16 * ks), g1 = *(const f32x4*)(qg + 16 * ks + 4);
; #pragma unroll
;                 for (int e = 0; e < 4; ++e) { qv[ks][e] *= rs * g0[e]; qv[ks][4 + e] *= rs * g1[e]; } }
; #pragma unroll
;             for (int k2 = 0; k2 < 2; ++k2) {
;                 const f32x4 c0 = *(const f32x4*)(cM + 16 * k2), c1 = *(const f32x4*)(cM + 16 * k2 + 4), s0 = *(const f32x4*)(sM + 16 * k2), s1 = *(const f32x4*)(sM + 16 * k2 + 4);
	flat_load_dwordx4 v[4:7], v[142:143]
	flat_load_dwordx4 v[0:3], v[142:143] offset:16
	v_pk_add_f32 v[104:105], v[106:107], v[104:105] op_sel_hi:[0,1]
	v_pk_fma_f32 v[104:105], v[188:189], v[188:189], v[104:105]
	v_mul_f32_e32 v106, v189, v189
	v_pk_add_f32 v[104:105], v[106:107], v[104:105] op_sel_hi:[0,1]
	v_pk_fma_f32 v[104:105], v[190:191], v[190:191], v[104:105]
	v_mul_f32_e32 v106, v191, v191
	v_pk_add_f32 v[104:105], v[106:107], v[104:105] op_sel_hi:[0,1]
	v_pk_fma_f32 v[104:105], v[186:187], v[186:187], v[104:105]
	v_mul_f32_e32 v106, v187, v187
	v_and_b32_e32 v123, 0xffff0000, v135
	v_lshlrev_b32_e32 v122, 16, v135
	v_and_b32_e32 v121, 0xffff0000, v141
	v_lshlrev_b32_e32 v120, 16, v141
	v_and_b32_e32 v129, 0xffff0000, v134
	v_lshlrev_b32_e32 v128, 16, v134
	v_and_b32_e32 v125, 0xffff0000, v140
	v_lshlrev_b32_e32 v124, 16, v140
	v_and_b32_e32 v135, 0xffff0000, v181
	v_lshlrev_b32_e32 v134, 16, v181
	v_and_b32_e32 v141, 0xffff0000, v180
	v_lshlrev_b32_e32 v140, 16, v180
	v_and_b32_e32 v181, 0xffff0000, v185
	v_lshlrev_b32_e32 v180, 16, v185
	v_and_b32_e32 v185, 0xffff0000, v184
	v_lshlrev_b32_e32 v184, 16, v184
	v_pk_add_f32 v[104:105], v[106:107], v[104:105] op_sel_hi:[0,1]
	v_pk_fma_f32 v[104:105], v[184:185], v[184:185], v[104:105]
	v_mul_f32_e32 v106, v185, v185
	v_pk_add_f32 v[104:105], v[106:107], v[104:105] op_sel_hi:[0,1]
	v_pk_fma_f32 v[104:105], v[180:181], v[180:181], v[104:105]
	v_mul_f32_e32 v106, v181, v181
	v_pk_add_f32 v[104:105], v[106:107], v[104:105] op_sel_hi:[0,1]
	v_pk_fma_f32 v[104:105], v[182:183], v[182:183], v[104:105]
	v_mul_f32_e32 v106, v183, v183
	v_pk_add_f32 v[104:105], v[106:107], v[104:105] op_sel_hi:[0,1]
	v_pk_fma_f32 v[104:105], v[178:179], v[178:179], v[104:105]
	v_mul_f32_e32 v106, v179, v179
	v_pk_add_f32 v[104:105], v[106:107], v[104:105] op_sel_hi:[0,1]
	v_pk_fma_f32 v[104:105], v[176:177], v[176:177], v[104:105]
	v_mul_f32_e32 v106, v177, v177
	v_pk_add_f32 v[104:105], v[106:107], v[104:105] op_sel_hi:[0,1]
	v_pk_fma_f32 v[104:105], v[172:173], v[172:173], v[104:105]
	v_mul_f32_e32 v106, v173, v173
	v_pk_add_f32 v[104:105], v[106:107], v[104:105] op_sel_hi:[0,1]
	v_pk_fma_f32 v[104:105], v[170:171], v[170:171], v[104:105]
	v_mul_f32_e32 v106, v171, v171
	v_pk_add_f32 v[104:105], v[106:107], v[104:105] op_sel_hi:[0,1]
	v_pk_fma_f32 v[104:105], v[138:139], v[138:139], v[104:105]
	v_mul_f32_e32 v106, v139, v139
	v_pk_add_f32 v[104:105], v[106:107], v[104:105] op_sel_hi:[0,1]
	v_pk_fma_f32 v[104:105], v[136:137], v[136:137], v[104:105]
	v_mul_f32_e32 v106, v137, v137
	v_pk_add_f32 v[104:105], v[106:107], v[104:105] op_sel_hi:[0,1]
	v_pk_fma_f32 v[104:105], v[130:131], v[130:131], v[104:105]
	v_mul_f32_e32 v106, v131, v131
	v_pk_add_f32 v[104:105], v[106:107], v[104:105] op_sel_hi:[0,1]
	v_pk_fma_f32 v[104:105], v[128:129], v[128:129], v[104:105]
	v_mul_f32_e32 v106, v129, v129
	v_pk_add_f32 v[104:105], v[106:107], v[104:105] op_sel_hi:[0,1]
	v_pk_fma_f32 v[104:105], v[122:123], v[122:123], v[104:105]
	v_mul_f32_e32 v106, v123, v123
	v_pk_add_f32 v[104:105], v[106:107], v[104:105] op_sel_hi:[0,1]
	v_pk_fma_f32 v[104:105], v[174:175], v[174:175], v[104:105]
	v_mul_f32_e32 v106, v175, v175
	v_pk_add_f32 v[104:105], v[106:107], v[104:105] op_sel_hi:[0,1]
	v_pk_fma_f32 v[104:105], v[168:169], v[168:169], v[104:105]
	v_mul_f32_e32 v106, v169, v169
	v_pk_add_f32 v[104:105], v[106:107], v[104:105] op_sel_hi:[0,1]
	v_pk_fma_f32 v[104:105], v[140:141], v[140:141], v[104:105]
	v_mul_f32_e32 v106, v141, v141
	v_pk_add_f32 v[104:105], v[106:107], v[104:105] op_sel_hi:[0,1]
	v_pk_fma_f32 v[104:105], v[134:135], v[134:135], v[104:105]
	v_mul_f32_e32 v106, v135, v135
	v_pk_add_f32 v[104:105], v[106:107], v[104:105] op_sel_hi:[0,1]
	v_pk_fma_f32 v[104:105], v[132:133], v[132:133], v[104:105]
	v_mul_f32_e32 v106, v133, v133
	v_pk_add_f32 v[104:105], v[106:107], v[104:105] op_sel_hi:[0,1]
	v_pk_fma_f32 v[104:105], v[126:127], v[126:127], v[104:105]
	v_mul_f32_e32 v106, v127, v127
	v_pk_add_f32 v[104:105], v[106:107], v[104:105] op_sel_hi:[0,1]
	v_pk_fma_f32 v[104:105], v[124:125], v[124:125], v[104:105]
	v_mul_f32_e32 v106, v125, v125
	v_pk_add_f32 v[104:105], v[106:107], v[104:105] op_sel_hi:[0,1]
	v_pk_fma_f32 v[104:105], v[120:121], v[120:121], v[104:105]
	v_mul_f32_e32 v106, v121, v121
	v_pk_add_f32 v[104:105], v[106:107], v[104:105] op_sel_hi:[0,1]
	v_mov_b32_e32 v105, v104
	s_nop 1
	v_permlane32_swap_b32_e32 v104, v105
	v_add_f32_e32 v104, v104, v105
	v_fmamk_f32 v104, v104, 0x3baaaaab, v225
	v_rsq_f32_e32 v227, v104
	flat_load_dwordx4 v[104:107], v[246:247]
	flat_load_dwordx4 v[228:231], v[246:247] offset:16
	v_mul_f32_e32 v248, 0x3dd53b94, v227
	s_waitcnt vmcnt(0) lgkmcnt(0)
; __device__ __forceinline__ void att_mfma(const Params& P, LAS unsigned char* lds, int wave) {
;     ...
;             const float rs = __builtin_amdgcn_rsqf(sq * (1.f / 192.f) + EPS) * (0.07216878364870322f * 1.4426950408889634f);
;             const float* qg = (const float*)(ws + WS_SMALL) + 2048 + 8 * hf;
;             const int spos = (int)(qrow_g & (SEQ - 1));
;             const float* cM = (const float*)(ws + WS_ROPE_M) + spos * 32 + 8 * hf; const float* sM = cM + 4096 * 32;
; #pragma unroll
;             for (int ks = 0; ks < 12; ++ks) { const f32x4 g0 = *(const f32x4*)(qg + 16 * ks), g1 = *(const f32x4*)(qg + 16 * ks + 4);
; #pragma unroll
;                 for (int e = 0; e < 4; ++e) { qv[ks][e] *= rs * g0[e]; qv[ks][4 + e] *= rs * g1[e]; } }
; #pragma unroll
;             for (int k2 = 0; k2 < 2; ++k2) {
;                 const f32x4 c0 = *(const f32x4*)(cM + 16 * k2), c1 = *(const f32x4*)(cM + 16 * k2 + 4), s0 = *(const f32x4*)(sM + 16 * k2), s1 = *(const f32x4*)(sM + 16 * k2 + 4);
; #pragma unroll
;                 for (int e = 0; e < 8; ++e) { const float cc = e < 4 ? c0[e & 3] : c1[e & 3], ss = e < 4 ? s0[e & 3] : s1[e & 3];
;                     const float a = qv[8 + k2][e], bq = qv[10 + k2][e]; qv[8 + k2][e] = a * cc - bq * ss; qv[10 + k2][e] = bq * cc + a * ss; }
	v_pk_mul_f32 v[96:97], v[96:97], v[248:249] op_sel_hi:[1,0]
	v_pk_mul_f32 v[100:101], v[100:101], v[248:249] op_sel_hi:[1,0]
	v_pk_mul_f32 v[252:253], v[96:97], v[232:233]
	v_pk_mul_f32 v[96:97], v[102:103], v[248:249] op_sel_hi:[1,0]
	v_pk_mul_f32 v[250:251], v[100:101], v[234:235]
	flat_load_dwordx4 v[232:235], v[142:143] offset:64
	flat_load_dwordx4 v[236:239], v[142:143] offset:80
	v_pk_mul_f32 v[142:143], v[96:97], v[242:243]
	v_pk_mul_f32 v[242:243], v[98:99], v[248:249] op_sel_hi:[1,0]
	flat_load_dwordx4 v[96:99], v[246:247] offset:64
	flat_load_dwordx4 v[100:103], v[246:247] offset:80
	v_pk_mul_f32 v[20:21], v[248:249], v[20:21] op_sel_hi:[0,1]
	v_pk_mul_f32 v[92:93], v[92:93], v[248:249] op_sel_hi:[1,0]
	v_pk_mul_f32 v[36:37], v[248:249], v[36:37] op_sel_hi:[0,1]
	v_pk_mul_f32 v[20:21], v[20:21], v[174:175]
	v_pk_mul_f32 v[92:93], v[92:93], v[108:109]
	v_pk_mul_f32 v[36:37], v[36:37], v[176:177]
	v_pk_mul_f32 v[38:39], v[248:249], v[38:39] op_sel_hi:[0,1]
	v_pk_mul_f32 v[24:25], v[248:249], v[24:25] op_sel_hi:[0,1]
	v_pk_mul_f32 v[22:23], v[248:249], v[22:23] op_sel_hi:[0,1]
	v_pk_mul_f32 v[38:39], v[38:39], v[172:173]
	v_pk_mul_f32 v[24:25], v[24:25], v[128:129]
	v_pk_mul_f32 v[16:17], v[248:249], v[16:17] op_sel_hi:[0,1]
	v_pk_mul_f32 v[22:23], v[22:23], v[168:169]
	v_pk_mul_f32 v[32:33], v[248:249], v[32:33] op_sel_hi:[0,1]
	v_pk_mul_f32 v[16:17], v[16:17], v[140:141]
	v_pk_mul_f32 v[32:33], v[32:33], v[170:171]
	v_pk_mul_f32 v[34:35], v[248:249], v[34:35] op_sel_hi:[0,1]
	v_pk_mul_f32 v[18:19], v[248:249], v[18:19] op_sel_hi:[0,1]
	v_pk_mul_f32 v[34:35], v[34:35], v[138:139]
	v_pk_mul_f32 v[18:19], v[18:19], v[134:135]
	v_pk_mul_f32 v[12:13], v[248:249], v[12:13] op_sel_hi:[0,1]
	v_pk_mul_f32 v[28:29], v[248:249], v[28:29] op_sel_hi:[0,1]
	v_pk_mul_f32 v[12:13], v[12:13], v[132:133]
	v_pk_mul_f32 v[28:29], v[28:29], v[136:137]
	v_pk_mul_f32 v[14:15], v[248:249], v[14:15] op_sel_hi:[0,1]
	v_pk_mul_f32 v[30:31], v[248:249], v[30:31] op_sel_hi:[0,1]
	v_pk_mul_f32 v[14:15], v[14:15], v[126:127]
	v_pk_mul_f32 v[30:31], v[30:31], v[130:131]
	v_pk_mul_f32 v[8:9], v[248:249], v[8:9] op_sel_hi:[0,1]
	v_pk_mul_f32 v[8:9], v[8:9], v[124:125]
	v_pk_mul_f32 v[10:11], v[248:249], v[10:11] op_sel_hi:[0,1]
	v_pk_mul_f32 v[26:27], v[248:249], v[26:27] op_sel_hi:[0,1]
	v_pk_mul_f32 v[10:11], v[10:11], v[120:121]
	v_pk_mul_f32 v[26:27], v[26:27], v[122:123]
	v_pk_mul_f32 v[60:61], v[248:249], v[60:61] op_sel_hi:[0,1]
	v_pk_mul_f32 v[56:57], v[248:249], v[56:57] op_sel_hi:[0,1]
	v_pk_mul_f32 v[62:63], v[248:249], v[62:63] op_sel_hi:[0,1]
	v_pk_mul_f32 v[58:59], v[248:249], v[58:59] op_sel_hi:[0,1]
	v_pk_mul_f32 v[52:53], v[248:249], v[52:53] op_sel_hi:[0,1]
	v_pk_mul_f32 v[48:49], v[248:249], v[48:49] op_sel_hi:[0,1]
	v_pk_mul_f32 v[54:55], v[248:249], v[54:55] op_sel_hi:[0,1]
	v_pk_mul_f32 v[50:51], v[248:249], v[50:51] op_sel_hi:[0,1]
	v_pk_mul_f32 v[44:45], v[248:249], v[44:45] op_sel_hi:[0,1]
	v_pk_mul_f32 v[40:41], v[248:249], v[40:41] op_sel_hi:[0,1]
	v_pk_mul_f32 v[46:47], v[248:249], v[46:47] op_sel_hi:[0,1]
	v_pk_mul_f32 v[42:43], v[248:249], v[42:43] op_sel_hi:[0,1]
	v_pk_mul_f32 v[88:89], v[88:89], v[248:249] op_sel_hi:[1,0]
	v_pk_mul_f32 v[94:95], v[94:95], v[248:249] op_sel_hi:[1,0]
	v_pk_mul_f32 v[90:91], v[90:91], v[248:249] op_sel_hi:[1,0]
	v_pk_mul_f32 v[84:85], v[84:85], v[248:249] op_sel_hi:[1,0]
	v_pk_mul_f32 v[80:81], v[248:249], v[80:81] op_sel_hi:[0,1]
	v_pk_mul_f32 v[86:87], v[86:87], v[248:249] op_sel_hi:[1,0]
	v_pk_mul_f32 v[82:83], v[248:249], v[82:83] op_sel_hi:[0,1]
	v_pk_mul_f32 v[76:77], v[248:249], v[76:77] op_sel_hi:[0,1]
	v_pk_mul_f32 v[72:73], v[248:249], v[72:73] op_sel_hi:[0,1]
	v_pk_mul_f32 v[78:79], v[248:249], v[78:79] op_sel_hi:[0,1]
	v_pk_mul_f32 v[74:75], v[248:249], v[74:75] op_sel_hi:[0,1]
	v_pk_mul_f32 v[68:69], v[248:249], v[68:69] op_sel_hi:[0,1]
	v_pk_mul_f32 v[64:65], v[248:249], v[64:65] op_sel_hi:[0,1]
	v_pk_mul_f32 v[70:71], v[248:249], v[70:71] op_sel_hi:[0,1]
	v_pk_mul_f32 v[66:67], v[248:249], v[66:67] op_sel_hi:[0,1]
	v_pk_mul_f32 v[60:61], v[60:61], v[200:201]
	v_pk_mul_f32 v[56:57], v[56:57], v[198:199]
	v_pk_mul_f32 v[62:63], v[62:63], v[196:197]
	v_pk_mul_f32 v[58:59], v[58:59], v[194:195]
	v_pk_mul_f32 v[52:53], v[52:53], v[192:193]
	v_pk_mul_f32 v[108:109], v[20:21], v[104:105]
	v_pk_mul_f32 v[48:49], v[48:49], v[190:191]
	v_pk_fma_f32 v[128:129], v[36:37], v[4:5], v[108:109] neg_lo:[0,0,1] neg_hi:[0,0,1]
	v_pk_mul_f32 v[36:37], v[36:37], v[104:105]
	v_pk_mul_f32 v[54:55], v[54:55], v[188:189]
	v_pk_fma_f32 v[4:5], v[20:21], v[4:5], v[36:37]
	v_pk_mul_f32 v[20:21], v[22:23], v[106:107]
	v_pk_mul_f32 v[36:37], v[38:39], v[106:107]
	v_pk_fma_f32 v[20:21], v[38:39], v[6:7], v[20:21] neg_lo:[0,0,1] neg_hi:[0,0,1]
	v_pk_fma_f32 v[6:7], v[22:23], v[6:7], v[36:37]
	v_pk_mul_f32 v[22:23], v[16:17], v[228:229]
	v_pk_mul_f32 v[50:51], v[50:51], v[186:187]
	v_pk_fma_f32 v[22:23], v[32:33], v[0:1], v[22:23] neg_lo:[0,0,1] neg_hi:[0,0,1]
	v_pk_mul_f32 v[32:33], v[32:33], v[228:229]
	v_pk_mul_f32 v[44:45], v[44:45], v[184:185]
	v_pk_fma_f32 v[0:1], v[16:17], v[0:1], v[32:33]
	v_pk_mul_f32 v[16:17], v[18:19], v[230:231]
	v_pk_mul_f32 v[32:33], v[34:35], v[230:231]
	v_pk_fma_f32 v[16:17], v[34:35], v[2:3], v[16:17] neg_lo:[0,0,1] neg_hi:[0,0,1]
	v_pk_fma_f32 v[2:3], v[18:19], v[2:3], v[32:33]
	s_waitcnt vmcnt(0) lgkmcnt(0)
; __device__ __forceinline__ void att_mfma(const Params& P, LAS unsigned char* lds, int wave) {
;     ...
;             for (int ks = 0; ks < 12; ++ks) { const f32x4 g0 = *(const f32x4*)(qg + 16 * ks), g1 = *(const f32x4*)(qg + 16 * ks + 4);
; #pragma unroll
;                 for (int e = 0; e < 4; ++e) { qv[ks][e] *= rs * g0[e]; qv[ks][4 + e] *= rs * g1[e]; } }
; #pragma unroll
;             for (int k2 = 0; k2 < 2; ++k2) {
;                 const f32x4 c0 = *(const f32x4*)(cM + 16 * k2), c1 = *(const f32x4*)(cM + 16 * k2 + 4), s0 = *(const f32x4*)(sM + 16 * k2), s1 = *(const f32x4*)(sM + 16 * k2 + 4);
; #pragma unroll
;                 for (int e = 0; e < 8; ++e) { const float cc = e < 4 ? c0[e & 3] : c1[e & 3], ss = e < 4 ? s0[e & 3] : s1[e & 3];
;                     const float a = qv[8 + k2][e], bq = qv[10 + k2][e]; qv[8 + k2][e] = a * cc - bq * ss; qv[10 + k2][e] = bq * cc + a * ss; }
;             }
; #pragma unroll
;             for (int ks = 0; ks < 12; ++ks) qf[ks] = pack8bf(qv[ks][0], qv[ks][1], qv[ks][2], qv[ks][3], qv[ks][4], qv[ks][5], qv[ks][6], qv[ks][7]);
;         }
;         int bcur = 0, bprev = 2, bnext = 1;
	v_pk_mul_f32 v[18:19], v[12:13], v[96:97]
	v_pk_mul_f32 v[40:41], v[40:41], v[182:183]
	v_pk_fma_f32 v[18:19], v[28:29], v[232:233], v[18:19] neg_lo:[0,0,1] neg_hi:[0,0,1]
	v_pk_mul_f32 v[28:29], v[28:29], v[96:97]
	v_pk_mul_f32 v[46:47], v[46:47], v[180:181]
	v_pk_fma_f32 v[12:13], v[12:13], v[232:233], v[28:29]
	v_pk_mul_f32 v[28:29], v[14:15], v[98:99]
	v_pk_mul_f32 v[42:43], v[42:43], v[178:179]
	v_pk_fma_f32 v[28:29], v[30:31], v[234:235], v[28:29] neg_lo:[0,0,1] neg_hi:[0,0,1]
	v_pk_mul_f32 v[30:31], v[30:31], v[98:99]
	v_pk_mul_f32 v[240:241], v[242:243], v[240:241]
	v_pk_fma_f32 v[14:15], v[14:15], v[234:235], v[30:31]
	v_pk_mul_f32 v[30:31], v[8:9], v[100:101]
	v_cvt_pk_bf16_f32 v141, v14, v15
	v_pk_fma_f32 v[30:31], v[24:25], v[236:237], v[30:31] neg_lo:[0,0,1] neg_hi:[0,0,1]
	v_pk_mul_f32 v[24:25], v[24:25], v[100:101]
	v_mov_b32_e32 v14, v165
	v_pk_fma_f32 v[8:9], v[8:9], v[236:237], v[24:25]
	v_pk_mul_f32 v[24:25], v[10:11], v[102:103]
	v_mov_b32_e32 v15, v165
	v_pk_fma_f32 v[24:25], v[26:27], v[238:239], v[24:25] neg_lo:[0,0,1] neg_hi:[0,0,1]
	v_pk_mul_f32 v[26:27], v[26:27], v[102:103]
	v_pk_mul_f32 v[88:89], v[88:89], v[220:221]
	v_pk_fma_f32 v[10:11], v[10:11], v[238:239], v[26:27]
	v_pk_mul_f32 v[94:95], v[94:95], v[110:111]
	v_pk_mul_f32 v[90:91], v[90:91], v[218:219]
	v_pk_mul_f32 v[84:85], v[84:85], v[112:113]
	v_pk_mul_f32 v[80:81], v[80:81], v[216:217]
	v_pk_mul_f32 v[86:87], v[86:87], v[114:115]
	v_pk_mul_f32 v[82:83], v[82:83], v[214:215]
	v_pk_mul_f32 v[76:77], v[76:77], v[116:117]
	v_pk_mul_f32 v[72:73], v[72:73], v[212:213]
	v_pk_mul_f32 v[78:79], v[78:79], v[118:119]
	v_pk_mul_f32 v[74:75], v[74:75], v[210:211]
	v_pk_mul_f32 v[68:69], v[68:69], v[208:209]
	v_pk_mul_f32 v[64:65], v[64:65], v[206:207]
	v_pk_mul_f32 v[70:71], v[70:71], v[204:205]
	v_pk_mul_f32 v[66:67], v[66:67], v[202:203]
	v_cvt_pk_bf16_f32 v97, v142, v143
	v_cvt_pk_bf16_f32 v116, v60, v61
	v_cvt_pk_bf16_f32 v117, v62, v63
	v_cvt_pk_bf16_f32 v118, v56, v57
	v_cvt_pk_bf16_f32 v119, v58, v59
	v_cvt_pk_bf16_f32 v120, v52, v53
	v_cvt_pk_bf16_f32 v121, v54, v55
	v_cvt_pk_bf16_f32 v122, v48, v49
	v_cvt_pk_bf16_f32 v123, v50, v51
	v_cvt_pk_bf16_f32 v124, v44, v45
	v_cvt_pk_bf16_f32 v125, v46, v47
	v_cvt_pk_bf16_f32 v126, v40, v41
	v_cvt_pk_bf16_f32 v127, v42, v43
	v_cvt_pk_bf16_f32 v128, v128, v129
	v_cvt_pk_bf16_f32 v129, v20, v21
	v_cvt_pk_bf16_f32 v130, v22, v23
	v_cvt_pk_bf16_f32 v131, v16, v17
	v_cvt_pk_bf16_f32 v132, v18, v19
	v_cvt_pk_bf16_f32 v133, v28, v29
	v_cvt_pk_bf16_f32 v134, v30, v31
	v_cvt_pk_bf16_f32 v135, v24, v25
	v_cvt_pk_bf16_f32 v136, v4, v5
	v_cvt_pk_bf16_f32 v137, v6, v7
	v_cvt_pk_bf16_f32 v138, v0, v1
	v_cvt_pk_bf16_f32 v139, v2, v3
	v_cvt_pk_bf16_f32 v140, v12, v13
	v_cvt_pk_bf16_f32 v142, v8, v9
	v_cvt_pk_bf16_f32 v143, v10, v11
	v_mov_b32_e32 v0, v165
	v_mov_b32_e32 v1, v165
	v_mov_b32_e32 v2, v165
	v_mov_b32_e32 v3, v165
	v_mov_b32_e32 v4, v165
	v_mov_b32_e32 v5, v165
	v_mov_b32_e32 v6, v165
	v_mov_b32_e32 v7, v165
	v_mov_b32_e32 v8, v165
	v_mov_b32_e32 v9, v165
	v_mov_b32_e32 v10, v165
	v_mov_b32_e32 v11, v165
	v_mov_b32_e32 v12, v165
	v_mov_b32_e32 v13, v165
	v_mov_b64_e32 v[30:31], v[14:15]
	v_mov_b64_e32 v[46:47], v[14:15]
	v_mov_b64_e32 v[62:63], v[14:15]
	v_cvt_pk_bf16_f32 v96, v250, v251
	v_cvt_pk_bf16_f32 v98, v252, v253
	v_cvt_pk_bf16_f32 v99, v240, v241
	v_cvt_pk_bf16_f32 v100, v92, v93
	v_cvt_pk_bf16_f32 v101, v94, v95
	v_cvt_pk_bf16_f32 v102, v88, v89
	v_cvt_pk_bf16_f32 v103, v90, v91
	v_cvt_pk_bf16_f32 v104, v84, v85
	v_cvt_pk_bf16_f32 v105, v86, v87
	v_cvt_pk_bf16_f32 v106, v80, v81
	v_cvt_pk_bf16_f32 v107, v82, v83
	v_cvt_pk_bf16_f32 v108, v76, v77
	v_cvt_pk_bf16_f32 v109, v78, v79
	v_cvt_pk_bf16_f32 v110, v72, v73
	v_cvt_pk_bf16_f32 v111, v74, v75
	v_cvt_pk_bf16_f32 v112, v68, v69
	v_cvt_pk_bf16_f32 v113, v70, v71
	v_cvt_pk_bf16_f32 v114, v64, v65
	v_cvt_pk_bf16_f32 v115, v66, v67
	v_mov_b32_e32 v169, 0xf149f2ca
	v_mov_b32_e32 v168, 0
	v_mov_b32_e32 v64, 0
	v_mov_b32_e32 v65, 0
	v_mov_b32_e32 v66, 0
	v_mov_b32_e32 v67, 0
	v_mov_b32_e32 v68, 0
	v_mov_b32_e32 v69, 0
	v_mov_b32_e32 v70, 0
	v_mov_b32_e32 v71, 0
	v_mov_b32_e32 v72, 0
	v_mov_b32_e32 v73, 0
	v_mov_b32_e32 v74, 0
	v_mov_b32_e32 v75, 0
	v_mov_b32_e32 v76, 0
	v_mov_b32_e32 v77, 0
	v_mov_b32_e32 v78, 0
	v_mov_b32_e32 v79, 0
	v_mov_b64_e32 v[28:29], v[12:13]
	v_mov_b64_e32 v[26:27], v[10:11]
	v_mov_b64_e32 v[24:25], v[8:9]
	v_mov_b64_e32 v[22:23], v[6:7]
	v_mov_b64_e32 v[20:21], v[4:5]
	v_mov_b64_e32 v[18:19], v[2:3]
	v_mov_b64_e32 v[16:17], v[0:1]
	v_mov_b64_e32 v[44:45], v[12:13]
	v_mov_b64_e32 v[42:43], v[10:11]
	v_mov_b64_e32 v[40:41], v[8:9]
	v_mov_b64_e32 v[38:39], v[6:7]
	v_mov_b64_e32 v[36:37], v[4:5]
	v_mov_b64_e32 v[34:35], v[2:3]
	v_mov_b64_e32 v[32:33], v[0:1]
	v_mov_b64_e32 v[60:61], v[12:13]
	v_mov_b64_e32 v[58:59], v[10:11]
	v_mov_b64_e32 v[56:57], v[8:9]
	v_mov_b64_e32 v[54:55], v[6:7]
	v_mov_b64_e32 v[52:53], v[4:5]
	v_mov_b64_e32 v[50:51], v[2:3]
	v_mov_b64_e32 v[48:49], v[0:1]
	v_mov_b32_e32 v196, 0
	v_mov_b32_e32 v197, 0
	v_mov_b32_e32 v198, 0
	v_mov_b32_e32 v199, 0
	v_mov_b32_e32 v200, 0
	v_mov_b32_e32 v201, 0
	v_mov_b32_e32 v202, 0
	v_mov_b32_e32 v203, 0
	v_mov_b32_e32 v204, 0
	v_mov_b32_e32 v205, 0
	v_mov_b32_e32 v206, 0
	v_mov_b32_e32 v207, 0
	v_mov_b32_e32 v208, 0
	v_mov_b32_e32 v209, 0
	v_mov_b32_e32 v210, 0
	v_mov_b32_e32 v211, 0
	v_mov_b32_e32 v212, 0x7149f2ca
	s_add_i32 s60, s16, 1
	s_add_i32 s81, s16, 2
	s_cmp_ge_u32 s81, s50
	s_mov_b32 s59, s61
	s_mov_b32 s83, 0
	s_cbranch_scc1 .LBB0_1016

; #define LAS __attribute__((address_space(3)))
; __device__ __forceinline__ void att_qk_sm(const LAS unsigned char* kb, int klane, const bf16x8 (&qf)[12], f32x16 (&o)[4], float& mrun, float& lrun, bf16x8 (&pb)[4]) {
;     constexpr int KP = 400;
;     f32x16 s0, s1;
; #pragma unroll
;     for (int i = 0; i < 16; ++i) { s0[i] = 0.f; s1[i] = 0.f; }
;     bf16x8 ka[3][2];
; #pragma unroll
;     for (int g = 0; g < 2; ++g) { ka[g][0] = *(const LAS bf16x8*)(kb + klane + g * 32); ka[g][1] = *(const LAS bf16x8*)(kb + klane + 32 * KP + g * 32); }
; #pragma unroll
;     for (int g = 0; g < 12; ++g) {
;         if (g < 10) { ka[(g + 2) % 3][0] = *(const LAS bf16x8*)(kb + klane + (g + 2) * 32); ka[(g + 2) % 3][1] = *(const LAS bf16x8*)(kb + klane + 32 * KP + (g + 2) * 32); }
;         __builtin_amdgcn_sched_barrier(0);
;         s0 = __builtin_amdgcn_mfma_f32_32x32x16_bf16(ka[g % 3][0], qf[g], s0, 0, 0, 0);
;         s1 = __builtin_amdgcn_mfma_f32_32x32x16_bf16(ka[g % 3][1], qf[g], s1, 0, 0, 0);
;         __builtin_amdgcn_sched_barrier(0);
;     }
.LBB0_1018:
	s_cmp_gt_u32 s16, s6
	s_cselect_b64 s[16:17], -1, 0
	s_and_b64 vcc, exec, s[16:17]
	s_cbranch_vccnz .Latt_skipq
	v_add_u32_e32 v194, s74, v223
	ds_read_b128 v[64:67], v194
	ds_read_b128 v[68:71], v194 offset:12800
	ds_read_b128 v[170:173], v194 offset:32
	ds_read_b128 v[174:177], v194 offset:12832
	ds_read_b128 v[182:185], v194 offset:64
	ds_read_b128 v[178:181], v194 offset:12864
	s_waitcnt lgkmcnt(4)
	v_mfma_f32_32x32x16_bf16 v[80:95], v[64:67], v[96:99], v[196:211]
	v_mfma_f32_32x32x16_bf16 v[64:79], v[68:71], v[96:99], v[196:211]
	ds_read_b128 v[186:189], v194 offset:96
	ds_read_b128 v[190:193], v194 offset:12896
	s_waitcnt lgkmcnt(4)
	v_mfma_f32_32x32x16_bf16 v[80:95], v[170:173], v[100:103], v[80:95]
	v_mfma_f32_32x32x16_bf16 v[64:79], v[174:177], v[100:103], v[64:79]
	ds_read_b128 v[170:173], v194 offset:128
	ds_read_b128 v[174:177], v194 offset:12928
	s_waitcnt lgkmcnt(4)
	v_mfma_f32_32x32x16_bf16 v[80:95], v[182:185], v[104:107], v[80:95]
	v_mfma_f32_32x32x16_bf16 v[64:79], v[178:181], v[104:107], v[64:79]
	ds_read_b128 v[178:181], v194 offset:160
	ds_read_b128 v[182:185], v194 offset:12960
	s_waitcnt lgkmcnt(4)
	v_mfma_f32_32x32x16_bf16 v[80:95], v[186:189], v[108:111], v[80:95]
	v_mfma_f32_32x32x16_bf16 v[64:79], v[190:193], v[108:111], v[64:79]
	ds_read_b128 v[186:189], v194 offset:192
	ds_read_b128 v[190:193], v194 offset:12992
	s_waitcnt lgkmcnt(4)
	v_mfma_f32_32x32x16_bf16 v[80:95], v[170:173], v[112:115], v[80:95]
	v_mfma_f32_32x32x16_bf16 v[64:79], v[174:177], v[112:115], v[64:79]
	ds_read_b128 v[170:173], v194 offset:224
	ds_read_b128 v[174:177], v194 offset:13024
	s_waitcnt lgkmcnt(4)
	v_mfma_f32_32x32x16_bf16 v[80:95], v[178:181], v[116:119], v[80:95]
	v_mfma_f32_32x32x16_bf16 v[64:79], v[182:185], v[116:119], v[64:79]
	ds_read_b128 v[178:181], v194 offset:256
	ds_read_b128 v[182:185], v194 offset:13056
	s_waitcnt lgkmcnt(4)
	v_mfma_f32_32x32x16_bf16 v[80:95], v[186:189], v[120:123], v[80:95]
	v_mfma_f32_32x32x16_bf16 v[64:79], v[190:193], v[120:123], v[64:79]
	ds_read_b128 v[186:189], v194 offset:288
	ds_read_b128 v[190:193], v194 offset:13088
	s_waitcnt lgkmcnt(4)
	v_mfma_f32_32x32x16_bf16 v[80:95], v[170:173], v[124:127], v[80:95]
	v_mfma_f32_32x32x16_bf16 v[64:79], v[174:177], v[124:127], v[64:79]
	ds_read_b128 v[170:173], v194 offset:320
	ds_read_b128 v[174:177], v194 offset:13120
	s_waitcnt lgkmcnt(4)
	v_mfma_f32_32x32x16_bf16 v[80:95], v[178:181], v[128:131], v[80:95]
	v_mfma_f32_32x32x16_bf16 v[64:79], v[182:185], v[128:131], v[64:79]
	ds_read_b128 v[178:181], v194 offset:352
	ds_read_b128 v[182:185], v194 offset:13152
	s_waitcnt lgkmcnt(4)
	v_mfma_f32_32x32x16_bf16 v[80:95], v[186:189], v[132:135], v[80:95]
	v_mfma_f32_32x32x16_bf16 v[64:79], v[190:193], v[132:135], v[64:79]
	s_waitcnt lgkmcnt(2)
	v_mfma_f32_32x32x16_bf16 v[80:95], v[170:173], v[136:139], v[80:95]
	v_mfma_f32_32x32x16_bf16 v[64:79], v[174:177], v[136:139], v[64:79]
	s_waitcnt lgkmcnt(0)
	v_mfma_f32_32x32x16_bf16 v[80:95], v[178:181], v[140:143], v[80:95]
	v_mfma_f32_32x32x16_bf16 v[64:79], v[182:185], v[140:143], v[64:79]
	s_cmp_lg_u32 s83, 0
	s_cbranch_scc0 .Latt_noissue_q
	s_mov_b64 s[4:5], s[10:11]
	s_cmp_eq_u32 s33, 0
	s_cselect_b32 s82, s76, s80
	s_add_i32 m0, s76, s19
	v_lshl_add_u64 v[172:173], s[4:5], 0, v[144:145]
	global_load_lds_dwordx4 v[172:173], off
	s_add_i32 m0, s76, s20
	v_lshl_add_u64 v[172:173], s[4:5], 0, v[146:147]
	global_load_lds_dwordx4 v[172:173], off
	s_add_i32 m0, s76, s21
	v_lshl_add_u64 v[172:173], s[4:5], 0, v[148:149]
	global_load_lds_dwordx4 v[172:173], off
	s_add_i32 m0, s82, s22
	v_lshl_add_u64 v[172:173], s[4:5], 0, v[150:151]
	global_load_lds_dwordx4 v[172:173], off
	s_add_i32 m0, s80, s23
	v_lshl_add_u64 v[172:173], s[4:5], 0, v[156:157]
	global_load_lds_dwordx4 v[172:173], off
	s_add_i32 m0, s80, s24
	v_lshl_add_u64 v[172:173], s[4:5], 0, v[154:155]
	global_load_lds_dwordx4 v[172:173], off
	s_branch .Latt_issued_q

; __device__ __forceinline__ void att_qk_sm(const LAS unsigned char* kb, int klane, const bf16x8 (&qf)[12], f32x16 (&o)[4], float& mrun, float& lrun, bf16x8 (&pb)[4]) {
;     ...
;     float mx = fmaxf(s0[0], s1[0]);
; #pragma unroll
;     for (int i = 1; i < 16; ++i) asm("v_max3_f32 %0, %1, %2, %3" : "=v"(mx) : "v"(mx), "v"(s0[i]), "v"(s1[i]));
;     { const auto rr = __builtin_amdgcn_permlane32_swap(__float_as_uint(mx), __float_as_uint(mx), false, false);
;       mx = fmaxf(__uint_as_float(rr[0]), __uint_as_float(rr[1])); }
;     if (!__all(mx - mrun <= 8.0f)) {
;         const float mn = fmaxf(mrun, mx), al = __builtin_amdgcn_exp2f(mrun - mn);
;         mrun = mn; lrun *= al;
; #pragma unroll
;         for (int d = 0; d < 4; ++d) o[d] = o[d] * al;
;     }
;     float ps = 0.f;
; #pragma unroll
;     for (int i = 0; i < 16; ++i) { s0[i] = __builtin_amdgcn_exp2f(s0[i] - mrun); s1[i] = __builtin_amdgcn_exp2f(s1[i] - mrun); ps += s0[i] + s1[i]; }
;     lrun += ps;
;     pb[0] = pack8bf(s0[0], s0[1], s0[2], s0[3], s0[4], s0[5], s0[6], s0[7]);
;     pb[1] = pack8bf(s0[8], s0[9], s0[10], s0[11], s0[12], s0[13], s0[14], s0[15]);
;     pb[2] = pack8bf(s1[0], s1[1], s1[2], s1[3], s1[4], s1[5], s1[6], s1[7]);
;     pb[3] = pack8bf(s1[8], s1[9], s1[10], s1[11], s1[12], s1[13], s1[14], s1[15]);
.Latt_issued_q:
	v_max_f32_e32 v170, v64, v80
	v_max3_f32 v170, v170, v81, v65
	v_max3_f32 v170, v170, v82, v66
	v_max3_f32 v170, v170, v83, v67
	v_max3_f32 v170, v170, v84, v68
	v_max3_f32 v170, v170, v85, v69
	v_max3_f32 v170, v170, v86, v70
	v_max3_f32 v170, v170, v87, v71
	v_max3_f32 v170, v170, v88, v72
	v_max3_f32 v170, v170, v89, v73
	v_max3_f32 v170, v170, v90, v74
	v_max3_f32 v170, v170, v91, v75
	v_max3_f32 v170, v170, v92, v76
	v_max3_f32 v170, v170, v93, v77
	v_max3_f32 v170, v170, v94, v78
	v_max3_f32 v170, v170, v95, v79
	v_mov_b32_e32 v171, v170
	s_nop 1
	v_permlane32_swap_b32_e32 v170, v171
	v_max_f32_e32 v170, v170, v171
	v_add_f32_e32 v171, v170, v212
	v_cmp_ge_f32_e32 vcc, s37, v171
	s_cmp_eq_u64 vcc, exec
	s_cbranch_scc1 .LBB0_1021
	v_sub_f32_e32 v170, v170, v196
	v_max_f32_e32 v171, v169, v170
	v_sub_f32_e32 v169, v169, v171
	v_add_f32_e32 v213, v171, v196
	v_exp_f32_e32 v170, v169
	v_mov_b32_e32 v169, v171
	v_mov_b32_e32 v212, 0
	v_sub_f32_e32 v196, 0, v171
	v_mul_f32_e32 v168, v168, v170
	v_mov_b32_e32 v197, v196
	v_mov_b32_e32 v198, v196
	v_mov_b32_e32 v199, v196
	v_mov_b32_e32 v200, v196
	v_mov_b32_e32 v201, v196
	v_mov_b32_e32 v202, v196
	v_mov_b32_e32 v203, v196
	v_mov_b32_e32 v204, v196
	v_mov_b32_e32 v205, v196
	v_mov_b32_e32 v206, v196
	v_mov_b32_e32 v207, v196
	v_mov_b32_e32 v208, v196
	v_mov_b32_e32 v209, v196
	v_mov_b32_e32 v210, v196
	v_mov_b32_e32 v211, v196
	v_sub_f32_e32 v80, v80, v213
	v_sub_f32_e32 v81, v81, v213
	v_sub_f32_e32 v82, v82, v213
	v_sub_f32_e32 v83, v83, v213
	v_sub_f32_e32 v84, v84, v213
	v_sub_f32_e32 v85, v85, v213
	v_sub_f32_e32 v86, v86, v213
	v_sub_f32_e32 v87, v87, v213
	v_sub_f32_e32 v88, v88, v213
	v_sub_f32_e32 v89, v89, v213
	v_sub_f32_e32 v90, v90, v213
	v_sub_f32_e32 v91, v91, v213
	v_sub_f32_e32 v92, v92, v213
	v_sub_f32_e32 v93, v93, v213
	v_sub_f32_e32 v94, v94, v213
	v_sub_f32_e32 v95, v95, v213
	v_sub_f32_e32 v64, v64, v213
	v_sub_f32_e32 v65, v65, v213
	v_sub_f32_e32 v66, v66, v213
	v_sub_f32_e32 v67, v67, v213
	v_sub_f32_e32 v68, v68, v213
	v_sub_f32_e32 v69, v69, v213
	v_sub_f32_e32 v70, v70, v213
	v_sub_f32_e32 v71, v71, v213
	v_sub_f32_e32 v72, v72, v213
	v_sub_f32_e32 v73, v73, v213
	v_sub_f32_e32 v74, v74, v213
	v_sub_f32_e32 v75, v75, v213
	v_sub_f32_e32 v76, v76, v213
	v_sub_f32_e32 v77, v77, v213
	v_sub_f32_e32 v78, v78, v213
	v_sub_f32_e32 v79, v79, v213
	v_pk_mul_f32 v[62:63], v[62:63], v[170:171] op_sel_hi:[1,0]
	v_pk_mul_f32 v[60:61], v[60:61], v[170:171] op_sel_hi:[1,0]
	v_pk_mul_f32 v[58:59], v[58:59], v[170:171] op_sel_hi:[1,0]
	v_pk_mul_f32 v[56:57], v[56:57], v[170:171] op_sel_hi:[1,0]
	v_pk_mul_f32 v[54:55], v[54:55], v[170:171] op_sel_hi:[1,0]
	v_pk_mul_f32 v[52:53], v[52:53], v[170:171] op_sel_hi:[1,0]
	v_pk_mul_f32 v[50:51], v[50:51], v[170:171] op_sel_hi:[1,0]
	v_pk_mul_f32 v[48:49], v[48:49], v[170:171] op_sel_hi:[1,0]
	v_pk_mul_f32 v[46:47], v[46:47], v[170:171] op_sel_hi:[1,0]
	v_pk_mul_f32 v[44:45], v[44:45], v[170:171] op_sel_hi:[1,0]
	v_pk_mul_f32 v[42:43], v[42:43], v[170:171] op_sel_hi:[1,0]
	v_pk_mul_f32 v[40:41], v[40:41], v[170:171] op_sel_hi:[1,0]
	v_pk_mul_f32 v[38:39], v[38:39], v[170:171] op_sel_hi:[1,0]
	v_pk_mul_f32 v[36:37], v[36:37], v[170:171] op_sel_hi:[1,0]
	v_pk_mul_f32 v[34:35], v[34:35], v[170:171] op_sel_hi:[1,0]
	v_pk_mul_f32 v[32:33], v[32:33], v[170:171] op_sel_hi:[1,0]
	v_pk_mul_f32 v[30:31], v[30:31], v[170:171] op_sel_hi:[1,0]
	v_pk_mul_f32 v[28:29], v[28:29], v[170:171] op_sel_hi:[1,0]
	v_pk_mul_f32 v[26:27], v[26:27], v[170:171] op_sel_hi:[1,0]
	v_pk_mul_f32 v[24:25], v[24:25], v[170:171] op_sel_hi:[1,0]
	v_pk_mul_f32 v[22:23], v[22:23], v[170:171] op_sel_hi:[1,0]
	v_pk_mul_f32 v[20:21], v[20:21], v[170:171] op_sel_hi:[1,0]
	v_pk_mul_f32 v[18:19], v[18:19], v[170:171] op_sel_hi:[1,0]
	v_pk_mul_f32 v[16:17], v[16:17], v[170:171] op_sel_hi:[1,0]
	v_pk_mul_f32 v[14:15], v[14:15], v[170:171] op_sel_hi:[1,0]
	v_pk_mul_f32 v[12:13], v[12:13], v[170:171] op_sel_hi:[1,0]
	v_pk_mul_f32 v[10:11], v[10:11], v[170:171] op_sel_hi:[1,0]
	v_pk_mul_f32 v[8:9], v[8:9], v[170:171] op_sel_hi:[1,0]
	v_pk_mul_f32 v[6:7], v[6:7], v[170:171] op_sel_hi:[1,0]
	v_pk_mul_f32 v[4:5], v[4:5], v[170:171] op_sel_hi:[1,0]
	v_pk_mul_f32 v[2:3], v[2:3], v[170:171] op_sel_hi:[1,0]
	v_pk_mul_f32 v[0:1], v[0:1], v[170:171] op_sel_hi:[1,0]
.LBB0_1021:
	v_exp_f32_e32 v80, v80
	v_exp_f32_e32 v81, v81
	v_exp_f32_e32 v82, v82
	v_exp_f32_e32 v83, v83
	v_exp_f32_e32 v84, v84
	v_exp_f32_e32 v85, v85
	v_exp_f32_e32 v86, v86
	v_exp_f32_e32 v87, v87
	v_exp_f32_e32 v88, v88
	v_exp_f32_e32 v89, v89
	v_exp_f32_e32 v90, v90
	v_exp_f32_e32 v91, v91
	v_exp_f32_e32 v92, v92
	v_exp_f32_e32 v93, v93
	v_exp_f32_e32 v94, v94
	v_exp_f32_e32 v95, v95
	v_exp_f32_e32 v64, v64
	v_exp_f32_e32 v65, v65
	v_exp_f32_e32 v66, v66
	v_exp_f32_e32 v67, v67
	v_exp_f32_e32 v68, v68
	v_exp_f32_e32 v69, v69
	v_exp_f32_e32 v70, v70
	v_exp_f32_e32 v71, v71
	v_exp_f32_e32 v72, v72
	v_exp_f32_e32 v73, v73
	v_exp_f32_e32 v74, v74
	v_exp_f32_e32 v75, v75
	v_exp_f32_e32 v76, v76
	v_exp_f32_e32 v77, v77
	v_exp_f32_e32 v78, v78
	v_exp_f32_e32 v79, v79
	v_pk_add_f32 v[172:173], v[80:81], v[82:83]
	v_pk_add_f32 v[174:175], v[84:85], v[86:87]
	v_pk_add_f32 v[176:177], v[88:89], v[90:91]
	v_pk_add_f32 v[178:179], v[92:93], v[94:95]
	v_pk_add_f32 v[172:173], v[172:173], v[64:65]
	v_pk_add_f32 v[174:175], v[174:175], v[66:67]
	v_pk_add_f32 v[176:177], v[176:177], v[68:69]
	v_pk_add_f32 v[178:179], v[178:179], v[70:71]
	v_pk_add_f32 v[172:173], v[172:173], v[72:73]
	v_pk_add_f32 v[174:175], v[174:175], v[74:75]
	v_pk_add_f32 v[176:177], v[176:177], v[76:77]
	v_pk_add_f32 v[178:179], v[178:179], v[78:79]
	v_pk_add_f32 v[172:173], v[172:173], v[174:175]
	v_pk_add_f32 v[176:177], v[176:177], v[178:179]
	v_cvt_pk_bf16_f32 v71, v70, v71
	v_cvt_pk_bf16_f32 v70, v68, v69
	v_cvt_pk_bf16_f32 v69, v66, v67
	v_cvt_pk_bf16_f32 v68, v64, v65
	v_pk_add_f32 v[172:173], v[172:173], v[176:177]
	v_cvt_pk_bf16_f32 v64, v72, v73
	v_cvt_pk_bf16_f32 v65, v74, v75
	v_cvt_pk_bf16_f32 v66, v76, v77
	v_cvt_pk_bf16_f32 v67, v78, v79
	v_add_f32_e32 v170, v172, v173
	v_cvt_pk_bf16_f32 v72, v88, v89
	v_cvt_pk_bf16_f32 v73, v90, v91
	v_cvt_pk_bf16_f32 v74, v92, v93
	v_cvt_pk_bf16_f32 v75, v94, v95
	v_add_f32_e32 v168, v168, v170
	v_cvt_pk_bf16_f32 v76, v80, v81
	v_cvt_pk_bf16_f32 v77, v82, v83
	v_cvt_pk_bf16_f32 v78, v84, v85
	v_cvt_pk_bf16_f32 v79, v86, v87
